# P3: cmp-task interleave stride 2 instead of 4 so every wave's cmp tasks are done in the first half and the dynamic row hand-out balances the end
# baseline (speedup 1.0000x reference)
; __global__ void __launch_bounds__(NTHR, 2) fwd_kernel(Args a) {
;     ...
;         const int nrow = (MTOK - gw + NGW - 1) / NGW, ncmp = (8192 - gw + NGW - 1) / NGW;
;         const int stride = nrow > 0 && ncmp > 0 ? (nrow / ncmp > 0 ? nrow / ncmp : 1) : 1, phase = ((wave >> 2) * (stride >> 1) + (wave & 1)) % stride;
;         int ci = 0;
;         for (int i = 0; i < nrow || ci < ncmp; ++i) {
;             if (ci < ncmp && (i >= nrow || (i % stride) == phase)) { const int task = gw + ci * NGW; ++ci;
;                 cmp_task(Z, KCC, VCT, OCMP, SELM, task >> 9, (task >> 8) & 1, (task + 64 * (task >> 11)) & 255, lane); }
.LBB0_474:
	s_mov_b32 s69, 2
	v_cvt_f32_u32_e32 v1, s69
	s_add_u32 s21, s18, 0x6000000
	s_addc_u32 s68, s19, 0
	s_add_u32 s12, s18, 0x6800000
	v_rcp_iflag_f32_e32 v1, v1
	s_addc_u32 s13, s19, 0
	s_or_b64 s[4:5], s[8:9], s[10:11]
	s_andn2_b64 vcc, exec, s[4:5]
	v_mul_f32_e32 v1, 0x4f7ffffe, v1
	v_cvt_u32_f32_e32 v1, v1
	s_nop 0
	v_readfirstlane_b32 s59, v1
	s_cbranch_vccnz .LBB0_659
	v_lshlrev_b32_e32 v1, 6, v133
	v_or_b32_e32 v37, 47, v1
	v_or_b32_e32 v46, 31, v1
	v_or_b32_e32 v117, 63, v1
	v_add_u32_e32 v119, 0x4f, v1
	v_or_b32_e32 v39, 0xaf, v1
	v_or_b32_e32 v48, 0x9f, v1
	v_or_b32_e32 v202, 0xbf, v1
	v_add_u32_e32 v203, 0xcf, v1
	v_or_b32_e32 v47, 0x12f, v1
	v_or_b32_e32 v50, 0x11f, v1
	v_or_b32_e32 v204, 0x13f, v1
	v_add_u32_e32 v205, 0x14f, v1
	v_or_b32_e32 v49, 0x1af, v1
	v_or_b32_e32 v52, 0x19f, v1
	v_or_b32_e32 v206, 0x1bf, v1
	v_add_u32_e32 v207, 0x1cf, v1
	v_or_b32_e32 v51, 0x22f, v1
	v_or_b32_e32 v54, 0x21f, v1
	v_or_b32_e32 v208, 0x23f, v1
	v_add_u32_e32 v209, 0x24f, v1
	v_or_b32_e32 v53, 0x2af, v1
	v_or_b32_e32 v56, 0x29f, v1
	v_or_b32_e32 v210, 0x2bf, v1
	v_add_u32_e32 v211, 0x2cf, v1
	v_or_b32_e32 v55, 0x32f, v1
	v_or_b32_e32 v58, 0x31f, v1
	v_or_b32_e32 v212, 0x33f, v1
	v_add_u32_e32 v213, 0x34f, v1
	v_or_b32_e32 v57, 0x3af, v1
	v_or_b32_e32 v60, 0x39f, v1
	v_or_b32_e32 v216, 0x3bf, v1
	v_add_u32_e32 v217, 0x3cf, v1
	v_or_b32_e32 v59, 0x42f, v1
	v_or_b32_e32 v62, 0x41f, v1
	v_or_b32_e32 v218, 0x43f, v1
	v_add_u32_e32 v219, 0x44f, v1
	v_or_b32_e32 v61, 0x4af, v1
	v_or_b32_e32 v64, 0x49f, v1
	v_or_b32_e32 v220, 0x4bf, v1
	v_add_u32_e32 v221, 0x4cf, v1
	v_or_b32_e32 v63, 0x52f, v1
	v_or_b32_e32 v66, 0x51f, v1
	v_or_b32_e32 v222, 0x53f, v1
	v_add_u32_e32 v223, 0x54f, v1
	v_or_b32_e32 v65, 0x5af, v1
	v_or_b32_e32 v68, 0x59f, v1
	v_or_b32_e32 v224, 0x5bf, v1
	v_add_u32_e32 v225, 0x5cf, v1
	v_or_b32_e32 v67, 0x62f, v1
	v_or_b32_e32 v70, 0x61f, v1
	v_or_b32_e32 v226, 0x63f, v1
	v_add_u32_e32 v227, 0x64f, v1
	v_or_b32_e32 v69, 0x6af, v1
	v_or_b32_e32 v72, 0x69f, v1
	v_or_b32_e32 v228, 0x6bf, v1
	v_add_u32_e32 v229, 0x6cf, v1
	v_or_b32_e32 v71, 0x72f, v1
	v_or_b32_e32 v74, 0x71f, v1
	v_or_b32_e32 v230, 0x73f, v1
	v_add_u32_e32 v231, 0x74f, v1
	v_or_b32_e32 v73, 0x7af, v1
	v_or_b32_e32 v76, 0x79f, v1
	v_or_b32_e32 v232, 0x7bf, v1
	v_add_u32_e32 v233, 0x7cf, v1
	v_lshl_or_b32 v1, v214, 3, v133
	v_cmp_lt_u32_e64 s[16:17], 2, v1
	v_cmp_lt_u32_e64 s[26:27], 10, v1
	v_cmp_lt_u32_e64 s[38:39], 18, v1
	v_writelane_b32 v253, s16, 6
	v_mov_b32_e32 v43, 0
	v_lshlrev_b32_e32 v40, 1, v139
	v_writelane_b32 v253, s17, 7
	v_cmp_lt_u32_e64 s[16:17], 4, v1
	v_mov_b32_e32 v41, v43
	v_or_b32_e32 v2, 2, v1
	v_writelane_b32 v253, s16, 8
	v_lshl_add_u64 v[44:45], s[48:49], 0, v[40:41]
	v_cmp_lt_u32_e64 s[48:49], 4, v2
	v_writelane_b32 v253, s17, 9
	v_cmp_lt_u32_e64 s[16:17], 6, v1
	s_lshr_b32 s4, s78, 8
	s_lshr_b32 s5, s69, 1
	v_writelane_b32 v253, s16, 10
	s_mul_i32 s4, s5, s4
	s_bfe_u32 s5, s78, 0x10006
	v_writelane_b32 v253, s17, 11
	v_cmp_lt_u32_e64 s[16:17], 8, v1
	s_add_i32 s4, s4, s5
	s_sub_i32 s5, 0, s69
	v_writelane_b32 v253, s16, 12
	s_mul_i32 s5, s5, s59
	s_mul_hi_u32 s5, s59, s5
	v_writelane_b32 v253, s17, 13
	v_writelane_b32 v253, s26, 14
	s_add_i32 s59, s59, s5
	s_mul_hi_u32 s5, s4, s59
	v_writelane_b32 v253, s27, 15
	v_cmp_lt_u32_e64 s[26:27], 12, v1
	s_mul_i32 s5, s5, s69
	s_sub_i32 s4, s4, s5
	v_writelane_b32 v253, s26, 16
	s_sub_i32 s5, s4, s69
	s_cmp_ge_u32 s4, s69
	v_writelane_b32 v253, s27, 17
	v_cmp_lt_u32_e64 s[26:27], 14, v1
	s_cselect_b32 s4, s5, s4
	s_sub_i32 s5, s4, s69
	v_writelane_b32 v253, s26, 18
	v_cmp_ne_u32_e64 s[6:7], 0, v1
	v_lshlrev_b32_e64 v237, v1, 1
	v_writelane_b32 v253, s27, 19
	v_cmp_lt_u32_e64 s[26:27], 16, v1
	v_lshlrev_b32_e64 v238, v1, 4
	v_lshlrev_b32_e64 v239, v1, 16
	v_writelane_b32 v253, s26, 20
	v_lshlrev_b32_e64 v240, v1, 64
	s_cmp_ge_u32 s4, s69
	v_writelane_b32 v253, s27, 21
	v_writelane_b32 v253, s38, 22
	v_mov_b32_e32 v139, v43
	v_lshlrev_b32_e32 v88, 2, v135
	v_writelane_b32 v253, s39, 23
	v_cmp_lt_u32_e64 s[38:39], 20, v1
	v_lshlrev_b32_e32 v241, 2, v242
	v_cmp_eq_u32_e64 s[74:75], 0, v242
	v_writelane_b32 v253, s38, 24
	v_lshlrev_b32_e32 v242, 5, v135
	s_cselect_b32 s60, s5, s4
	v_writelane_b32 v253, s39, 25
	v_cmp_lt_u32_e64 s[38:39], 22, v1
	v_lshrrev_b32_e32 v113, 2, v134
	v_lshlrev_b32_e32 v115, 6, v214
	v_writelane_b32 v253, s38, 26
	v_lshlrev_b32_e32 v38, 6, v134
	v_lshl_add_u64 v[78:79], s[14:15], 0, v[138:139]
	v_writelane_b32 v253, s39, 27
	v_writelane_b32 v253, s48, 28
	v_cmp_eq_u32_e64 s[38:39], 25, v1
	v_or_b32_e32 v80, 0x1000, v136
	v_writelane_b32 v253, s49, 29
	v_cmp_lt_u32_e64 s[48:49], 5, v2
	v_cmp_gt_u32_e64 s[4:5], 32, v135
	v_or_b32_e32 v84, 20, v133
	v_writelane_b32 v253, s48, 30
	v_or_b32_e32 v36, 18, v133
	v_or_b32_e32 v236, 24, v133
	v_writelane_b32 v253, s49, 31
	v_cmp_lt_u32_e64 s[48:49], 6, v2
	v_or_b32_e32 v81, 28, v133
	s_mov_b32 s15, 0
	v_writelane_b32 v253, s48, 32
	v_cmp_lt_u32_e64 s[16:17], 1, v214
	v_cmp_ne_u32_e64 s[26:27], 0, v214
	v_writelane_b32 v253, s49, 33
	v_cmp_lt_u32_e64 s[48:49], 8, v2
	v_cmp_eq_u32_e64 s[28:29], 3, v214
	v_or_b32_e32 v83, 0x101, v88
	v_writelane_b32 v253, s48, 34
	v_or_b32_e32 v90, 0x100, v88
	v_or_b32_e32 v85, 0x103, v88
	v_writelane_b32 v253, s49, 35
	v_cmp_lt_u32_e64 s[48:49], 9, v2
	v_or_b32_e32 v92, 0x102, v88
	v_or_b32_e32 v87, 0x201, v88
	v_writelane_b32 v253, s48, 36
	v_or_b32_e32 v86, 0x200, v88
	v_or_b32_e32 v89, 0x203, v88
	v_writelane_b32 v253, s49, 37
	v_cmp_lt_u32_e64 s[48:49], 10, v2
	v_or_b32_e32 v91, 0x301, v88
	v_or_b32_e32 v98, 0x300, v88
	v_writelane_b32 v253, s48, 38
	v_or_b32_e32 v93, 0x303, v88
; DI void cmp_task(const bf16_t* Z, const bf16_t* KCC, const bf16_t* VCT, bf16_t* OCMP, unsigned* selm, int b, int hk, int tg, int lane) {
;     ...
;         unsigned word = 0u;
; #pragma unroll
;         for (int mm = 0; mm < 4; ++mm) {
;             const int jm = 8 * g + 2 * mm + h; const float v = mine[mm]; int rank = 0;
; #pragma unroll
;             for (int T = 0; T < 4; ++T)
; #pragma unroll
;                 for (int m2 = 0; m2 < 4; ++m2) { const int je = 8 * T + 2 * m2;
;                     rank += (ev[T][m2] > v || (ev[T][m2] == v && je < jm)) ? 1 : 0; rank += (od[T][m2] > v || (od[T][m2] == v && je + 1 < jm)) ? 1 : 0; }
;             if (v >= 0.f && rank < 5) word |= 1u << jm;
	v_or_b32_e32 v100, 0x302, v88
	v_writelane_b32 v253, s49, 39
	v_cmp_lt_u32_e64 s[48:49], 16, v2
	v_or_b32_e32 v102, 0x400, v88
	v_or_b32_e32 v104, 0x402, v88
	v_writelane_b32 v253, s48, 40
	v_or_b32_e32 v99, 0x501, v88
	v_or_b32_e32 v106, 0x500, v88
	v_writelane_b32 v253, s49, 41
	v_cmp_lt_u32_e64 s[48:49], 12, v2
	v_or_b32_e32 v101, 0x503, v88
	v_or_b32_e32 v108, 0x502, v88
	v_writelane_b32 v253, s48, 42
	v_or_b32_e32 v103, 0x601, v88
	v_or_b32_e32 v110, 0x600, v88
	v_writelane_b32 v253, s49, 43
	v_cmp_lt_u32_e64 s[48:49], 17, v2
	v_or_b32_e32 v105, 0x603, v88
	v_or_b32_e32 v112, 0x602, v88
	v_writelane_b32 v253, s48, 44
	v_or_b32_e32 v107, 0x701, v88
	v_or_b32_e32 v114, 0x700, v88
	v_writelane_b32 v253, s49, 45
	v_cmp_lt_u32_e64 s[48:49], 13, v2
	v_or_b32_e32 v109, 0x703, v88
	v_or_b32_e32 v116, 0x702, v88
	v_writelane_b32 v253, s48, 46
	v_or_b32_e32 v243, 31, v242
	s_mov_b32 s46, 0x3e38aa3b
	v_writelane_b32 v253, s49, 47
	v_cmp_lt_u32_e64 s[48:49], 18, v2
	s_mov_b32 s61, 0xff800000
	s_mov_b32 s62, -1.0
	v_writelane_b32 v253, s48, 48
	v_lshlrev_b32_e32 v120, 2, v88
	v_mov_b32_e32 v244, 0x2200
	v_writelane_b32 v253, s49, 49
	v_cmp_lt_u32_e64 s[48:49], 14, v2
	v_mov_b32_e32 v245, 0xff800000
	s_mov_b32 s63, 0
	v_writelane_b32 v253, s48, 50
	s_mov_b32 s64, 0
	s_nop 0
	v_writelane_b32 v253, s49, 51
	v_cmp_lt_u32_e64 s[48:49], 20, v2
	s_nop 1
	v_writelane_b32 v253, s48, 52
	s_nop 1
	v_writelane_b32 v253, s49, 53
	v_cmp_lt_u32_e64 s[48:49], 21, v2
	s_nop 1
	v_writelane_b32 v253, s48, 54
	s_nop 1
	v_writelane_b32 v253, s49, 55
	v_cmp_lt_u32_e64 s[48:49], 22, v2
	s_nop 1
	v_writelane_b32 v253, s48, 56
	s_nop 1
	v_writelane_b32 v253, s49, 57
	v_cmp_lt_u32_e64 s[48:49], 24, v2
	s_nop 1
	v_writelane_b32 v253, s48, 58
	s_nop 1
	v_writelane_b32 v253, s49, 59
	v_cmp_lt_u32_e64 s[48:49], 25, v2
	v_or_b32_e32 v2, 4, v1
	s_nop 0
	v_writelane_b32 v253, s48, 60
	s_nop 1
	v_writelane_b32 v253, s49, 61
	v_cmp_lt_u32_e64 s[48:49], 5, v2
	s_nop 1
	v_writelane_b32 v253, s48, 62
	s_nop 1
	v_writelane_b32 v253, s49, 63
	v_cmp_lt_u32_e64 s[48:49], 6, v2
	s_nop 1
	v_writelane_b32 v254, s48, 0
	s_nop 1
	v_writelane_b32 v254, s49, 1
	v_cmp_lt_u32_e64 s[48:49], 8, v2
	s_nop 1
	v_writelane_b32 v254, s48, 2
	s_nop 1
	v_writelane_b32 v254, s49, 3
	v_cmp_lt_u32_e64 s[48:49], 9, v2
	s_nop 1
	v_writelane_b32 v254, s48, 4
	s_nop 1
	v_writelane_b32 v254, s49, 5
	v_cmp_lt_u32_e64 s[48:49], 10, v2
	s_nop 1
	v_writelane_b32 v254, s48, 6
	s_nop 1
	v_writelane_b32 v254, s49, 7
	v_cmp_lt_u32_e64 s[48:49], 11, v2
	s_nop 1
	v_writelane_b32 v254, s48, 8
	s_nop 1
	v_writelane_b32 v254, s49, 9
	v_cmp_lt_u32_e64 s[48:49], 12, v2
	s_nop 1
	v_writelane_b32 v254, s48, 10
	s_nop 1
	v_writelane_b32 v254, s49, 11
	v_cmp_lt_u32_e64 s[48:49], 13, v2
	s_nop 1
	v_writelane_b32 v254, s48, 12
	s_nop 1
	v_writelane_b32 v254, s49, 13
	v_cmp_lt_u32_e64 s[48:49], 14, v2
	s_nop 1
	v_writelane_b32 v254, s48, 14
	s_nop 1
	v_writelane_b32 v254, s49, 15
	v_cmp_lt_u32_e64 s[48:49], 16, v2
	s_nop 1
	v_writelane_b32 v254, s48, 16
	s_nop 1
	v_writelane_b32 v254, s49, 17
	v_cmp_lt_u32_e64 s[48:49], 17, v2
	s_nop 1
	v_writelane_b32 v254, s48, 18
	s_nop 1
	v_writelane_b32 v254, s49, 19
	v_cmp_lt_u32_e64 s[48:49], 18, v2
	s_nop 1
	v_writelane_b32 v254, s48, 20
	s_nop 1
	v_writelane_b32 v254, s49, 21
	v_cmp_lt_u32_e64 s[48:49], 19, v2
	s_nop 1
	v_writelane_b32 v254, s48, 22
	s_nop 1
	v_writelane_b32 v254, s49, 23
	v_cmp_lt_u32_e64 s[48:49], 20, v2
	s_nop 1
	v_writelane_b32 v254, s48, 24
	s_nop 1
	v_writelane_b32 v254, s49, 25
	v_cmp_lt_u32_e64 s[48:49], 21, v2
	s_nop 1
	v_writelane_b32 v254, s48, 26
	s_nop 1
	v_writelane_b32 v254, s49, 27
	v_cmp_lt_u32_e64 s[48:49], 22, v2
	s_nop 1
	v_writelane_b32 v254, s48, 28
	s_nop 1
	v_writelane_b32 v254, s49, 29
	v_cmp_lt_u32_e64 s[48:49], 24, v2
	s_nop 1
	v_writelane_b32 v254, s48, 30
	s_nop 1
	v_writelane_b32 v254, s49, 31
	v_cmp_lt_u32_e64 s[48:49], 25, v2
	s_nop 1
	v_writelane_b32 v254, s48, 32
	s_nop 1
	v_writelane_b32 v254, s49, 33
	v_cmp_lt_u32_e64 s[48:49], 26, v2
	s_nop 1
	v_writelane_b32 v254, s48, 34
	s_nop 1
	v_writelane_b32 v254, s49, 35
	v_cmp_lt_u32_e64 s[48:49], 27, v2
	v_or_b32_e32 v2, 6, v1
	v_and_b32_e32 v1, 35, v0
	v_writelane_b32 v254, s48, 36
	v_cmp_lt_u32_e64 s[70:71], 29, v2
	v_cmp_eq_u32_e64 s[72:73], 0, v1
	v_writelane_b32 v254, s49, 37
	v_cmp_lt_u32_e64 s[48:49], 8, v2
	v_mbcnt_lo_u32_b32 v1, -1, 0
	v_mbcnt_hi_u32_b32 v246, -1, v1
	v_writelane_b32 v254, s48, 38
	s_nop 1
	v_writelane_b32 v254, s49, 39
	v_cmp_lt_u32_e64 s[48:49], 9, v2
	s_nop 1
	v_writelane_b32 v254, s48, 40
	s_nop 1
	v_writelane_b32 v254, s49, 41
	v_cmp_lt_u32_e64 s[48:49], 10, v2
	s_nop 1
	v_writelane_b32 v254, s48, 42
	s_nop 1
	v_writelane_b32 v254, s49, 43
	v_cmp_lt_u32_e64 s[48:49], 11, v2
	s_nop 1
	v_writelane_b32 v254, s48, 44
	s_nop 1
	v_writelane_b32 v254, s49, 45
	v_cmp_lt_u32_e64 s[48:49], 12, v2
	s_nop 1
	v_writelane_b32 v254, s48, 46
	s_nop 1
	v_writelane_b32 v254, s49, 47
	v_cmp_lt_u32_e64 s[48:49], 13, v2
	s_nop 1
	v_writelane_b32 v254, s48, 48
	s_nop 1
	v_writelane_b32 v254, s49, 49
	v_cmp_lt_u32_e64 s[48:49], 14, v2
	s_nop 1
	v_writelane_b32 v254, s48, 50
	s_nop 1
	v_writelane_b32 v254, s49, 51
	v_cmp_lt_u32_e64 s[48:49], 16, v2
	s_nop 1
	v_writelane_b32 v254, s48, 52
	s_nop 1
	v_writelane_b32 v254, s49, 53
	v_cmp_lt_u32_e64 s[48:49], 17, v2
	s_nop 1
	v_writelane_b32 v254, s48, 54
	s_nop 1
	v_writelane_b32 v254, s49, 55
	v_cmp_lt_u32_e64 s[48:49], 18, v2
	s_nop 1
	v_writelane_b32 v254, s48, 56
	s_nop 1
	v_writelane_b32 v254, s49, 57
	v_cmp_lt_u32_e64 s[48:49], 19, v2
	s_nop 1
	v_writelane_b32 v254, s48, 58
	s_nop 1
	v_writelane_b32 v254, s49, 59
	v_cmp_lt_u32_e64 s[48:49], 20, v2
	s_nop 1
	v_writelane_b32 v254, s48, 60
	s_nop 1
	v_writelane_b32 v254, s49, 61
	v_cmp_lt_u32_e64 s[48:49], 21, v2
	s_nop 1
	v_writelane_b32 v254, s48, 62
	s_nop 1
	v_writelane_b32 v254, s49, 63
	v_cmp_lt_u32_e64 s[48:49], 22, v2
	s_nop 1
	v_writelane_b32 v255, s48, 0
	s_nop 1
	v_writelane_b32 v255, s49, 1
	v_cmp_lt_u32_e64 s[48:49], 24, v2
	s_nop 1
	v_writelane_b32 v255, s48, 2
	s_nop 1
	v_writelane_b32 v255, s49, 3
	v_cmp_lt_u32_e64 s[48:49], 25, v2
	s_nop 1
	v_writelane_b32 v255, s48, 4
	s_nop 1
	v_writelane_b32 v255, s49, 5
	v_cmp_lt_u32_e64 s[48:49], 26, v2
	s_nop 1
	v_writelane_b32 v255, s48, 6
	s_nop 1
	v_writelane_b32 v255, s49, 7
	v_cmp_lt_u32_e64 s[48:49], 27, v2
	s_nop 1
	v_writelane_b32 v255, s48, 8
	s_nop 1
	v_writelane_b32 v255, s49, 9
	v_cmp_lt_u32_e64 s[48:49], 28, v2
	v_lshlrev_b64 v[2:3], v135, -1
	v_not_b32_e32 v111, v3
	v_writelane_b32 v255, s48, 10
	v_not_b32_e32 v118, v2
	s_nop 0
	v_writelane_b32 v255, s49, 11
	s_mov_b64 s[48:49], exec
	s_mov_b64 exec, 1
	v_mov_b32_e32 v1, 0
	v_mov_b32_e32 v2, 1
	ds_add_rtn_u32 v2, v1, v2
	s_waitcnt lgkmcnt(0)
	v_readfirstlane_b32 s47, v2
	s_mov_b64 exec, s[48:49]
	s_cmpk_lt_u32 s47, 0x80
	s_cselect_b64 s[8:9], -1, 0
	s_branch .LBB0_477
